# + m26: at XCD-local barriers the waiting workgroups poll the XCD arrival counter itself instead of the last arriver's release word (one atomic round trip + one add less on the release path); wait cond
# baseline (speedup 1.0000x reference)
; __device__ __forceinline__ unsigned xb_ld(unsigned* p)              { return __hip_atomic_load(p, __ATOMIC_RELAXED, __HIP_MEMORY_SCOPE_AGENT); }
; __device__ __forceinline__ unsigned xb_add(unsigned* p, unsigned v) { return __hip_atomic_fetch_add(p, v, __ATOMIC_RELAXED, __HIP_MEMORY_SCOPE_AGENT); }
; #define XB_SPIN(cond, bar) do { unsigned _sp = 0; while (cond) { __builtin_amdgcn_s_sleep(0); \
;     if ((++_sp & 255u) == 0u) { if (xb_ld(&(bar)[XB_TMO])) break; if (_sp > XB_SPIN_CAP) { atomicAdd(&(bar)[XB_TMO], 1u); break; } } } } while (0)
; __device__ __forceinline__ void xcd_barrier(const XcdBarrier& b) {
;     ...
;         const unsigned old = xb_add(&bar[XB_XSUB(b.x)], 1u);
;         const unsigned gen = old / nloc;
;         if (old + 1u == (gen + 1u) * nloc) {
;             __builtin_amdgcn_fence(__ATOMIC_RELEASE, "agent");
;             asm volatile("s_waitcnt vmcnt(0)" ::: "memory");
;             const unsigned og = xb_add(&bar[XB_TOP], 1u);
;             const unsigned tg = og / nx;
;             if (og + 1u == (tg + 1u) * nx) xb_add(&bar[XB_TOPGEN], 1u);
;             else XB_SPIN(xb_ld(&bar[XB_TOPGEN]) == tg, bar);
;             __builtin_amdgcn_fence(__ATOMIC_ACQUIRE, "agent");
;             xb_add(&bar[XB_XGEN(b.x)], 1u);
;             asm volatile("s_waitcnt vmcnt(0)" ::: "memory");
;         } else {
;             XB_SPIN(xb_ld(&bar[XB_XGEN(b.x)]) == gen, bar);
.LBB0_742:
	s_or_b64 exec, exec, s[12:13]
	v_cvt_f32_u32_e32 v4, v2
	s_waitcnt vmcnt(0)
	v_readfirstlane_b32 s1, v3
	v_sub_u32_e32 v3, 0, v2
	v_rcp_iflag_f32_e32 v4, v4
	v_add_u32_e32 v5, s1, v1
	v_mul_f32_e32 v4, 0x4f7ffffe, v4
	v_cvt_u32_f32_e32 v4, v4
	v_mul_lo_u32 v1, v3, v4
	v_mul_hi_u32 v1, v4, v1
	v_add_u32_e32 v1, v4, v1
	v_mul_hi_u32 v1, v5, v1
	v_mul_lo_u32 v3, v1, v2
	v_sub_u32_e32 v3, v5, v3
	v_add_u32_e32 v4, 1, v1
	v_cmp_ge_u32_e32 vcc, v3, v2
	s_nop 1
	v_cndmask_b32_e32 v1, v1, v4, vcc
	v_sub_u32_e32 v4, v3, v2
	v_cndmask_b32_e32 v3, v3, v4, vcc
	v_add_u32_e32 v4, 1, v1
	v_cmp_ge_u32_e32 vcc, v3, v2
	v_add_u32_e32 v3, 1, v5
	s_nop 0
	v_cndmask_b32_e32 v1, v1, v4, vcc
	v_mul_lo_u32 v4, v2, v1
	v_add_u32_e32 v2, v4, v2
	v_cmp_ne_u32_e32 vcc, v3, v2
	s_and_saveexec_b64 s[10:11], vcc
	s_xor_b64 s[10:11], exec, s[10:11]
	s_cbranch_execz .LBB0_756
	v_readlane_b32 s99, v255, 42
	s_cmp_ge_u32 s3, 18
	s_cselect_b32 s98, 18, 0
	s_sub_u32 s98, s3, s98
	s_mov_b32 s20, 0x2000
	s_cmp_eq_u32 s99, 0
	s_cbranch_scc1 .Lfull_f
	s_cmp_eq_u32 s98, 5
	s_cbranch_scc1 .Lloc_noinv
	s_cmp_eq_u32 s98, 6
	s_cbranch_scc1 .Lloc_noinv
	s_cmp_eq_u32 s98, 11
	s_cbranch_scc1 .Lloc_noinv
	s_cmp_eq_u32 s98, 1
	s_cbranch_scc1 .Lloc_inv
	s_cmp_eq_u32 s98, 4
	s_cbranch_scc1 .Lloc_inv
	s_cmp_eq_u32 s98, 7
	s_cbranch_scc1 .Lloc_inv
	s_cmp_eq_u32 s98, 10
	s_cbranch_scc1 .Lloc_inv
	s_cmp_eq_u32 s98, 14
	s_cbranch_scc1 .Lloc_inv
	s_cmp_eq_u32 s98, 16
	s_cbranch_scc1 .Lloc_inv
.Lfull_f:
	buffer_inv sc1
	s_branch .Lnf_f

; __device__ __forceinline__ unsigned xb_ld(unsigned* p)              { return __hip_atomic_load(p, __ATOMIC_RELAXED, __HIP_MEMORY_SCOPE_AGENT); }
; #define XB_SPIN(cond, bar) do { unsigned _sp = 0; while (cond) { __builtin_amdgcn_s_sleep(0); \
;     if ((++_sp & 255u) == 0u) { if (xb_ld(&(bar)[XB_TMO])) break; if (_sp > XB_SPIN_CAP) { atomicAdd(&(bar)[XB_TMO], 1u); break; } } } } while (0)
; __device__ __forceinline__ void xcd_barrier(const XcdBarrier& b) {
;     ...
;         } else {
;             XB_SPIN(xb_ld(&bar[XB_XGEN(b.x)]) == gen, bar);
.Lloc_noinv:
	s_mov_b32 s20, 0x1000
	v_add_u32_e32 v1, -1, v2
.Lnf_f:
	s_waitcnt lgkmcnt(0)
	v_mov_b32_e32 v0, s20
	global_load_dword v0, v0, s[8:9] offset:1024 sc1
	s_add_i32 s21, s20, 0x400
	s_add_u32 s16, s8, s21
	s_addc_u32 s17, s9, 0
	s_waitcnt vmcnt(0)
	v_cmp_le_u32_e32 vcc, v0, v1
	s_and_saveexec_b64 s[12:13], vcc
	s_cbranch_execz .LBB0_755
	s_add_u32 s14, s30, 0x80200
	s_addc_u32 s15, s31, 0
	s_mov_b32 s1, 1
	s_mov_b64 s[18:19], 0
	s_branch .LBB0_746

.LBB0_750:
	global_load_dword v0, v193, s[16:17] sc1
	s_add_i32 s1, s1, 1
	s_mov_b64 s[28:29], -1
	s_waitcnt vmcnt(0)
	v_cmp_gt_u32_e32 vcc, v0, v1
	s_orn2_b64 s[22:23], vcc, exec
	s_branch .LBB0_745
